# adds counted LDS waits in MLA attention P.V, batched bias loads in neighbourhood-attention mask fix-up, 64-bit accumulator zeroing; on top of fast f32 reciprocal for sigmoids and GEMM MFMA snake order
# speedup vs baseline: 1.0281x; 1.0029x over previous
.LBB0_94:
	v_mov_b64_e32 v[4:5], 0x1800
	s_ashr_i32 s9, s8, 31
	v_cmp_lt_i64_e32 vcc, s[10:11], v[4:5]
	s_lshl_b64 s[10:11], s[8:9], 20
	s_add_u32 s10, s22, s10
	s_addc_u32 s11, s23, s11
	s_and_b64 s[12:13], vcc, exec
	s_cselect_b32 s9, s11, s15
	s_cselect_b32 s37, s10, s14
	s_ashr_i32 s7, s6, 31
	s_lshl_b64 s[12:13], s[6:7], 20
	s_add_u32 s12, s24, s12
	s_addc_u32 s13, s25, s13
	s_and_b64 s[18:19], vcc, exec
	s_cselect_b32 s7, s13, s17
	s_cselect_b32 s38, s12, s16
	s_add_u32 s14, s14, 0x80080
	s_addc_u32 s15, s15, 0
	s_add_u32 s39, s16, 0x100
	s_addc_u32 s40, s17, 0
	s_mov_b32 s41, -2
	v_mov_b64_e32 v[4:5], 0
	v_mov_b64_e32 v[6:7], 0
	v_mov_b64_e32 v[8:9], 0
	v_mov_b64_e32 v[10:11], 0
	v_mov_b64_e32 v[12:13], 0
	v_mov_b64_e32 v[14:15], 0
	v_mov_b64_e32 v[16:17], 0
	v_mov_b64_e32 v[18:19], 0
	v_mov_b64_e32 v[20:21], 0
	v_mov_b64_e32 v[22:23], 0
	v_mov_b64_e32 v[24:25], 0
	v_mov_b64_e32 v[26:27], 0
	v_mov_b64_e32 v[28:29], 0
	v_mov_b64_e32 v[30:31], 0
	v_mov_b64_e32 v[32:33], 0
	v_mov_b64_e32 v[34:35], 0
	v_mov_b64_e32 v[36:37], 0
	v_mov_b64_e32 v[38:39], 0
	v_mov_b64_e32 v[40:41], 0
	v_mov_b64_e32 v[42:43], 0
	v_mov_b64_e32 v[44:45], 0
	v_mov_b64_e32 v[46:47], 0
	v_mov_b64_e32 v[48:49], 0
	v_mov_b64_e32 v[50:51], 0
	v_mov_b64_e32 v[52:53], 0
	v_mov_b64_e32 v[54:55], 0
	v_mov_b64_e32 v[56:57], 0
	v_mov_b64_e32 v[58:59], 0
	v_mov_b64_e32 v[60:61], 0
	v_mov_b64_e32 v[62:63], 0
	v_mov_b64_e32 v[64:65], 0
	v_mov_b64_e32 v[66:67], 0
	v_mov_b64_e32 v[68:69], 0
	v_mov_b64_e32 v[70:71], 0
	v_mov_b64_e32 v[72:73], 0
	v_mov_b64_e32 v[74:75], 0
	v_mov_b64_e32 v[76:77], 0
	v_mov_b64_e32 v[78:79], 0
	v_mov_b64_e32 v[80:81], 0
	v_mov_b64_e32 v[82:83], 0
	v_mov_b64_e32 v[84:85], 0
	v_mov_b64_e32 v[86:87], 0
	v_mov_b64_e32 v[88:89], 0
	v_mov_b64_e32 v[90:91], 0
	v_mov_b64_e32 v[92:93], 0
	v_mov_b64_e32 v[94:95], 0
	v_mov_b64_e32 v[96:97], 0
	v_mov_b64_e32 v[98:99], 0
	v_mov_b64_e32 v[100:101], 0
	v_mov_b64_e32 v[102:103], 0
	v_mov_b64_e32 v[104:105], 0
	v_mov_b64_e32 v[106:107], 0
	v_mov_b64_e32 v[108:109], 0
	v_mov_b64_e32 v[110:111], 0
	v_mov_b64_e32 v[112:113], 0
	v_mov_b64_e32 v[114:115], 0
	v_mov_b64_e32 v[116:117], 0
	v_mov_b64_e32 v[118:119], 0
	v_mov_b64_e32 v[120:121], 0
	v_mov_b64_e32 v[122:123], 0
	v_mov_b64_e32 v[124:125], 0
	v_mov_b64_e32 v[126:127], 0
	v_mov_b64_e32 v[128:129], 0
	v_mov_b64_e32 v[130:131], 0

.LBB0_235:
	v_mov_b64_e32 v[4:5], 0x340
	s_ashr_i32 s9, s8, 31
	v_cmp_lt_i64_e32 vcc, s[10:11], v[4:5]
	s_lshl_b64 s[10:11], s[8:9], 18
	s_add_u32 s10, s21, s10
	s_addc_u32 s11, s22, s11
	s_and_b64 s[12:13], vcc, exec
	s_cselect_b32 s9, s11, s15
	s_cselect_b32 s36, s10, s14
	s_ashr_i32 s7, s6, 31
	s_lshl_b64 s[12:13], s[6:7], 18
	s_add_u32 s12, s23, s12
	s_addc_u32 s13, s24, s13
	s_and_b64 s[18:19], vcc, exec
	s_cselect_b32 s7, s13, s17
	s_cselect_b32 s37, s12, s16
	s_add_u32 s14, s14, 0x20080
	s_addc_u32 s15, s15, 0
	s_add_u32 s38, s16, 0x100
	s_addc_u32 s39, s17, 0
	s_mov_b32 s40, -2
	v_mov_b64_e32 v[4:5], 0
	v_mov_b64_e32 v[6:7], 0
	v_mov_b64_e32 v[8:9], 0
	v_mov_b64_e32 v[10:11], 0
	v_mov_b64_e32 v[12:13], 0
	v_mov_b64_e32 v[14:15], 0
	v_mov_b64_e32 v[16:17], 0
	v_mov_b64_e32 v[18:19], 0
	v_mov_b64_e32 v[20:21], 0
	v_mov_b64_e32 v[22:23], 0
	v_mov_b64_e32 v[24:25], 0
	v_mov_b64_e32 v[26:27], 0
	v_mov_b64_e32 v[28:29], 0
	v_mov_b64_e32 v[30:31], 0
	v_mov_b64_e32 v[32:33], 0
	v_mov_b64_e32 v[34:35], 0
	v_mov_b64_e32 v[36:37], 0
	v_mov_b64_e32 v[38:39], 0
	v_mov_b64_e32 v[40:41], 0
	v_mov_b64_e32 v[42:43], 0
	v_mov_b64_e32 v[44:45], 0
	v_mov_b64_e32 v[46:47], 0
	v_mov_b64_e32 v[48:49], 0
	v_mov_b64_e32 v[50:51], 0
	v_mov_b64_e32 v[52:53], 0
	v_mov_b64_e32 v[54:55], 0
	v_mov_b64_e32 v[56:57], 0
	v_mov_b64_e32 v[58:59], 0
	v_mov_b64_e32 v[60:61], 0
	v_mov_b64_e32 v[62:63], 0
	v_mov_b64_e32 v[64:65], 0
	v_mov_b64_e32 v[66:67], 0
	v_mov_b64_e32 v[68:69], 0
	v_mov_b64_e32 v[70:71], 0
	v_mov_b64_e32 v[72:73], 0
	v_mov_b64_e32 v[74:75], 0
	v_mov_b64_e32 v[76:77], 0
	v_mov_b64_e32 v[78:79], 0
	v_mov_b64_e32 v[80:81], 0
	v_mov_b64_e32 v[82:83], 0
	v_mov_b64_e32 v[84:85], 0
	v_mov_b64_e32 v[86:87], 0
	v_mov_b64_e32 v[88:89], 0
	v_mov_b64_e32 v[90:91], 0
	v_mov_b64_e32 v[92:93], 0
	v_mov_b64_e32 v[94:95], 0
	v_mov_b64_e32 v[96:97], 0
	v_mov_b64_e32 v[98:99], 0
	v_mov_b64_e32 v[100:101], 0
	v_mov_b64_e32 v[102:103], 0
	v_mov_b64_e32 v[104:105], 0
	v_mov_b64_e32 v[106:107], 0
	v_mov_b64_e32 v[108:109], 0
	v_mov_b64_e32 v[110:111], 0
	v_mov_b64_e32 v[112:113], 0
	v_mov_b64_e32 v[114:115], 0
	v_mov_b64_e32 v[116:117], 0
	v_mov_b64_e32 v[118:119], 0
	v_mov_b64_e32 v[120:121], 0
	v_mov_b64_e32 v[122:123], 0
	v_mov_b64_e32 v[124:125], 0
	v_mov_b64_e32 v[126:127], 0
	v_mov_b64_e32 v[128:129], 0
	v_mov_b64_e32 v[130:131], 0

.LBB0_520:
	v_cndmask_b32_e64 v167, v145, v167, s[4:5]
	v_mul_f32_e32 v145, 0xbdd53b94, v167
	v_fmamk_f32 v84, v84, 0x3dd53b94, v145
	v_fmamk_f32 v85, v85, 0x3dd53b94, v145
	v_fmamk_f32 v86, v86, 0x3dd53b94, v145
	v_fmamk_f32 v87, v87, 0x3dd53b94, v145
	v_fmamk_f32 v88, v88, 0x3dd53b94, v145
	v_fmamk_f32 v89, v89, 0x3dd53b94, v145
	v_fmamk_f32 v90, v90, 0x3dd53b94, v145
	v_fmamk_f32 v91, v91, 0x3dd53b94, v145
	v_fmamk_f32 v92, v92, 0x3dd53b94, v145
	v_fmamk_f32 v93, v93, 0x3dd53b94, v145
	v_fmamk_f32 v94, v94, 0x3dd53b94, v145
	v_fmamk_f32 v95, v95, 0x3dd53b94, v145
	v_fmamk_f32 v96, v96, 0x3dd53b94, v145
	v_fmamk_f32 v97, v97, 0x3dd53b94, v145
	v_fmamk_f32 v98, v98, 0x3dd53b94, v145
	v_fmamk_f32 v99, v99, 0x3dd53b94, v145
	v_fmamk_f32 v68, v68, 0x3dd53b94, v145
	v_fmamk_f32 v69, v69, 0x3dd53b94, v145
	v_fmamk_f32 v70, v70, 0x3dd53b94, v145
	v_fmamk_f32 v71, v71, 0x3dd53b94, v145
	v_fmamk_f32 v72, v72, 0x3dd53b94, v145
	v_fmamk_f32 v73, v73, 0x3dd53b94, v145
	v_fmamk_f32 v74, v74, 0x3dd53b94, v145
	v_fmamk_f32 v75, v75, 0x3dd53b94, v145
	v_fmamk_f32 v76, v76, 0x3dd53b94, v145
	v_fmamk_f32 v77, v77, 0x3dd53b94, v145
	v_fmamk_f32 v78, v78, 0x3dd53b94, v145
	v_fmamk_f32 v79, v79, 0x3dd53b94, v145
	v_fmamk_f32 v80, v80, 0x3dd53b94, v145
	v_fmamk_f32 v81, v81, 0x3dd53b94, v145
	v_fmamk_f32 v82, v82, 0x3dd53b94, v145
	v_fmac_f32_e32 v145, 0x3dd53b94, v83
	v_exp_f32_e32 v83, v84
	v_exp_f32_e32 v84, v85
	v_exp_f32_e32 v85, v86
	v_exp_f32_e32 v86, v87
	v_exp_f32_e32 v87, v88
	v_exp_f32_e32 v88, v89
	v_exp_f32_e32 v89, v90
	v_exp_f32_e32 v90, v91
	v_exp_f32_e32 v91, v92
	v_exp_f32_e32 v92, v93
	v_exp_f32_e32 v93, v94
	v_exp_f32_e32 v94, v95
	v_exp_f32_e32 v95, v96
	v_exp_f32_e32 v96, v97
	v_exp_f32_e32 v97, v98
	v_exp_f32_e32 v98, v99
	v_exp_f32_e32 v99, v68
	v_add_f32_e32 v68, 0, v83
	v_add_f32_e32 v68, v84, v68
	v_add_f32_e32 v68, v85, v68
	v_add_f32_e32 v68, v86, v68
	v_add_f32_e32 v68, v87, v68
	v_add_f32_e32 v68, v88, v68
	v_add_f32_e32 v68, v89, v68
	v_add_f32_e32 v68, v90, v68
	v_add_f32_e32 v68, v91, v68
	v_add_f32_e32 v68, v92, v68
	v_add_f32_e32 v68, v93, v68
	v_add_f32_e32 v68, v94, v68
	v_add_f32_e32 v68, v95, v68
	v_exp_f32_e32 v69, v69
	v_add_f32_e32 v68, v96, v68
	v_exp_f32_e32 v147, v70
	v_add_f32_e32 v68, v97, v68
	v_exp_f32_e32 v151, v71
	v_add_f32_e32 v68, v98, v68
	v_exp_f32_e32 v153, v72
	v_add_f32_e32 v68, v99, v68
	v_exp_f32_e32 v169, v73
	v_add_f32_e32 v68, v69, v68
	v_exp_f32_e32 v170, v74
	v_add_f32_e32 v68, v147, v68
	v_exp_f32_e32 v171, v75
	v_add_f32_e32 v68, v151, v68
	v_exp_f32_e32 v172, v76
	v_add_f32_e32 v68, v153, v68
	v_exp_f32_e32 v173, v77
	v_add_f32_e32 v68, v169, v68
	v_exp_f32_e32 v174, v78
	v_add_f32_e32 v68, v170, v68
	v_exp_f32_e32 v175, v79
	v_add_f32_e32 v68, v171, v68
	v_exp_f32_e32 v176, v80
	v_add_f32_e32 v68, v172, v68
	v_exp_f32_e32 v177, v81
	v_add_f32_e32 v68, v173, v68
	v_exp_f32_e32 v178, v82
	v_add_f32_e32 v68, v174, v68
	v_exp_f32_e32 v145, v145
	v_add_f32_e32 v68, v175, v68
	v_add_f32_e32 v68, v176, v68
	v_add_f32_e32 v68, v177, v68
	v_add_f32_e32 v68, v178, v68
	v_add_f32_e32 v68, v145, v68
	v_mov_b32_e32 v70, v68
	s_nop 1
	v_permlane32_swap_b32_e32 v68, v70
	v_add_f32_e32 v68, v68, v70
	v_fmac_f32_e32 v68, v168, v2
	v_cvt_pk_bf16_f32 v70, v83, v84
	v_cvt_pk_bf16_f32 v71, v85, v86
	v_cvt_pk_bf16_f32 v72, v87, v88
	v_cvt_pk_bf16_f32 v73, v89, v90
	v_cvt_pk_bf16_f32 v74, v91, v92
	v_cvt_pk_bf16_f32 v75, v93, v94
	v_cvt_pk_bf16_f32 v76, v95, v96
	v_cvt_pk_bf16_f32 v77, v97, v98
	v_cvt_pk_bf16_f32 v78, v99, v69
	v_cvt_pk_bf16_f32 v79, v147, v151
	v_cvt_pk_bf16_f32 v80, v153, v169
	v_cvt_pk_bf16_f32 v81, v170, v171
	v_cvt_pk_bf16_f32 v82, v172, v173
	v_cvt_pk_bf16_f32 v83, v174, v175
	v_cvt_pk_bf16_f32 v84, v176, v177
	v_cvt_pk_bf16_f32 v85, v178, v145
	v_permlane32_swap_b32_e32 v70, v72
	v_permlane32_swap_b32_e32 v71, v73
	v_permlane32_swap_b32_e32 v74, v76
	v_permlane32_swap_b32_e32 v75, v77
	v_permlane32_swap_b32_e32 v78, v80
	v_permlane32_swap_b32_e32 v79, v81
	v_permlane32_swap_b32_e32 v82, v84
	v_permlane32_swap_b32_e32 v83, v85
	v_add_u32_e32 v2, s33, v166
	ds_read_b64_tr_b16 v[86:87], v2 offset:0
	ds_read_b64_tr_b16 v[88:89], v2 offset:0x800
	ds_read_b64_tr_b16 v[90:91], v2 offset:0x1000
	ds_read_b64_tr_b16 v[92:93], v2 offset:0x1800
	ds_read_b64_tr_b16 v[94:95], v2 offset:0x2000
	ds_read_b64_tr_b16 v[96:97], v2 offset:0x2800
	ds_read_b64_tr_b16 v[168:169], v2 offset:0x3000
	ds_read_b64_tr_b16 v[170:171], v2 offset:0x3800
	s_waitcnt lgkmcnt(6)
	s_nop 0
	v_mfma_f32_32x32x16_bf16 v[52:67], v[70:73], v[86:89], v[52:67]
	ds_read_b64_tr_b16 v[86:87], v2 offset:0x200
	ds_read_b64_tr_b16 v[88:89], v2 offset:0xa00
	s_waitcnt lgkmcnt(6)
	v_mfma_f32_32x32x16_bf16 v[52:67], v[74:77], v[90:93], v[52:67]
	ds_read_b64_tr_b16 v[90:91], v2 offset:0x1200
	ds_read_b64_tr_b16 v[92:93], v2 offset:0x1a00
	s_waitcnt lgkmcnt(6)
	v_mfma_f32_32x32x16_bf16 v[52:67], v[78:81], v[94:97], v[52:67]
	ds_read_b64_tr_b16 v[94:95], v2 offset:0x2200
	ds_read_b64_tr_b16 v[96:97], v2 offset:0x2a00
	s_waitcnt lgkmcnt(6)
	v_mfma_f32_32x32x16_bf16 v[52:67], v[82:85], v[168:171], v[52:67]
	ds_read_b64_tr_b16 v[168:169], v2 offset:0x3200
	ds_read_b64_tr_b16 v[170:171], v2 offset:0x3a00
	s_waitcnt lgkmcnt(6)
	v_mfma_f32_32x32x16_bf16 v[36:51], v[70:73], v[86:89], v[36:51]
	ds_read_b64_tr_b16 v[86:87], v2 offset:0x400
	ds_read_b64_tr_b16 v[88:89], v2 offset:0xc00
	s_waitcnt lgkmcnt(6)
	v_mfma_f32_32x32x16_bf16 v[36:51], v[74:77], v[90:93], v[36:51]
	ds_read_b64_tr_b16 v[90:91], v2 offset:0x1400
	ds_read_b64_tr_b16 v[92:93], v2 offset:0x1c00
	s_waitcnt lgkmcnt(6)
	v_mfma_f32_32x32x16_bf16 v[36:51], v[78:81], v[94:97], v[36:51]
	ds_read_b64_tr_b16 v[94:95], v2 offset:0x2400
	ds_read_b64_tr_b16 v[96:97], v2 offset:0x2c00
	s_waitcnt lgkmcnt(6)
	v_mfma_f32_32x32x16_bf16 v[36:51], v[82:85], v[168:171], v[36:51]
	ds_read_b64_tr_b16 v[168:169], v2 offset:0x3400
	ds_read_b64_tr_b16 v[170:171], v2 offset:0x3c00
	s_waitcnt lgkmcnt(6)
	v_mfma_f32_32x32x16_bf16 v[20:35], v[70:73], v[86:89], v[20:35]
	ds_read_b64_tr_b16 v[86:87], v2 offset:0x600
	ds_read_b64_tr_b16 v[88:89], v2 offset:0xe00
	s_waitcnt lgkmcnt(6)
	v_mfma_f32_32x32x16_bf16 v[20:35], v[74:77], v[90:93], v[20:35]
	ds_read_b64_tr_b16 v[90:91], v2 offset:0x1600
	ds_read_b64_tr_b16 v[92:93], v2 offset:0x1e00
	s_waitcnt lgkmcnt(6)
	v_mfma_f32_32x32x16_bf16 v[20:35], v[78:81], v[94:97], v[20:35]
	ds_read_b64_tr_b16 v[94:95], v2 offset:0x2600
	ds_read_b64_tr_b16 v[96:97], v2 offset:0x2e00
	s_waitcnt lgkmcnt(6)
	v_mfma_f32_32x32x16_bf16 v[20:35], v[82:85], v[168:171], v[20:35]
	ds_read_b64_tr_b16 v[168:169], v2 offset:0x3600
	ds_read_b64_tr_b16 v[170:171], v2 offset:0x3e00
	s_waitcnt lgkmcnt(6)
	v_mfma_f32_32x32x16_bf16 v[4:19], v[70:73], v[86:89], v[4:19]
	s_waitcnt vmcnt(0) lgkmcnt(0)
	s_cmpk_eq_i32 s31, 0x48
	s_waitcnt vmcnt(0)
	s_barrier
	v_mfma_f32_32x32x16_bf16 v[4:19], v[74:77], v[90:93], v[4:19]
	v_mfma_f32_32x32x16_bf16 v[4:19], v[78:81], v[94:97], v[4:19]
	v_mfma_f32_32x32x16_bf16 v[4:19], v[82:85], v[168:171], v[4:19]
	s_cbranch_scc0 .LBB0_512
	s_and_saveexec_b64 s[4:5], s[0:1]
	s_cbranch_execz .LBB0_497
	ds_write_b32 v159, v68
	s_branch .LBB0_497

.LBB0_557:
	s_andn2_b64 vcc, exec, s[30:31]
	s_cbranch_vccnz .LBB0_623
	s_add_i32 s4, s36, s41
	s_add_i32 s26, s4, -1
	s_cmp_ge_i32 s26, s16
	s_cselect_b64 s[4:5], -1, 0
	s_cmp_lt_i32 s26, s17
	s_cselect_b64 s[26:27], -1, 0
	s_and_b64 s[4:5], s[4:5], s[26:27]
	s_and_b64 s[26:27], s[4:5], exec
	s_cselect_b32 s26, s18, 0
	s_lshl_b32 s26, s26, 2
	v_readlane_b32 s30, v254, 63
	s_add_i32 s26, s26, 0
	v_readlane_b32 s31, v255, 0
	s_add_i32 s26, s26, 0x1c800
	v_lshl_add_u32 v68, v187, 2, s26
	ds_read_b32 v68, v68 offset:60
	v_lshl_add_u32 v154, v188, 2, s26
	ds_read_b32 v154, v154 offset:60
	v_lshl_add_u32 v69, v189, 2, s26
	ds_read_b32 v69, v69 offset:60
	v_lshl_add_u32 v155, v190, 2, s26
	ds_read_b32 v155, v155 offset:60
	v_lshl_add_u32 v70, v191, 2, s26
	ds_read_b32 v70, v70 offset:60
	v_lshl_add_u32 v156, v192, 2, s26
	ds_read_b32 v156, v156 offset:60
	v_lshl_add_u32 v71, v193, 2, s26
	ds_read_b32 v71, v71 offset:60
	v_lshl_add_u32 v157, v194, 2, s26
	ds_read_b32 v157, v157 offset:60
	v_lshl_add_u32 v72, v195, 2, s26
	ds_read_b32 v72, v72 offset:60
	v_lshl_add_u32 v158, v196, 2, s26
	ds_read_b32 v158, v158 offset:60
	v_lshl_add_u32 v73, v197, 2, s26
	ds_read_b32 v73, v73 offset:60
	v_lshl_add_u32 v159, v200, 2, s26
	ds_read_b32 v159, v159 offset:60
	v_lshl_add_u32 v74, v201, 2, s26
	ds_read_b32 v74, v74 offset:60
	v_lshl_add_u32 v160, v202, 2, s26
	ds_read_b32 v160, v160 offset:60
	v_lshl_add_u32 v75, v203, 2, s26
	ds_read_b32 v75, v75 offset:60
	v_lshl_add_u32 v161, v204, 2, s26
	ds_read_b32 v161, v161 offset:60
	v_lshl_add_u32 v76, v205, 2, s26
	ds_read_b32 v76, v76 offset:60
	v_lshl_add_u32 v162, v206, 2, s26
	ds_read_b32 v162, v162 offset:252
	v_lshl_add_u32 v77, v207, 2, s26
	ds_read_b32 v77, v77 offset:60
	v_lshl_add_u32 v163, v208, 2, s26
	ds_read_b32 v163, v163 offset:256
	v_lshl_add_u32 v78, v209, 2, s26
	ds_read_b32 v78, v78 offset:60
	v_lshl_add_u32 v164, v210, 2, s26
	ds_read_b32 v164, v164 offset:260
	v_lshl_add_u32 v79, v211, 2, s26
	ds_read_b32 v79, v79 offset:60
	v_lshl_add_u32 v165, v212, 2, s26
	ds_read_b32 v165, v165 offset:264
	v_lshl_add_u32 v80, v213, 2, s26
	ds_read_b32 v80, v80 offset:60
	v_lshl_add_u32 v166, v214, 2, s26
	ds_read_b32 v166, v166 offset:284
	v_lshl_add_u32 v81, v215, 2, s26
	ds_read_b32 v81, v81 offset:60
	v_lshl_add_u32 v167, v216, 2, s26
	ds_read_b32 v167, v167 offset:288
	v_lshl_add_u32 v82, v217, 2, s26
	ds_read_b32 v82, v82 offset:60
	v_lshl_add_u32 v151, v218, 2, s26
	ds_read_b32 v151, v151 offset:292
	v_lshl_add_u32 v83, v219, 2, s26
	ds_read_b32 v83, v83 offset:60
	v_lshl_add_u32 v153, v220, 2, s26
	ds_read_b32 v153, v153 offset:296
	s_waitcnt lgkmcnt(0)
	s_and_b64 s[46:47], s[4:5], s[30:31]
	v_fmac_f32_e32 v68, 0x3e0293ee, v100
	v_mov_b32_e32 v100, 0xff61b1e6
	s_mov_b64 vcc, s[46:47]
	v_cndmask_b32_e32 v68, v100, v68, vcc
	v_readlane_b32 s30, v255, 1
	v_readlane_b32 s31, v255, 2
	v_readlane_b32 s46, v255, 3
	s_and_b64 s[30:31], s[4:5], s[30:31]
	v_readlane_b32 s47, v255, 4
	s_and_b64 s[46:47], s[30:31], s[46:47]
	v_fmac_f32_e32 v154, 0x3e0293ee, v84
	s_mov_b64 vcc, s[46:47]
	v_cndmask_b32_e32 v154, v100, v154, vcc
	v_readlane_b32 s30, v255, 5
	v_readlane_b32 s31, v255, 6
	s_and_b64 s[46:47], s[4:5], s[30:31]
	v_fmac_f32_e32 v69, 0x3e0293ee, v101
	s_mov_b64 vcc, s[46:47]
	v_cndmask_b32_e32 v69, v100, v69, vcc
	v_readlane_b32 s30, v255, 7
	v_readlane_b32 s31, v255, 8
	v_readlane_b32 s46, v255, 9
	s_and_b64 s[30:31], s[4:5], s[30:31]
	v_readlane_b32 s47, v255, 10
	s_and_b64 s[46:47], s[30:31], s[46:47]
	v_fmac_f32_e32 v155, 0x3e0293ee, v85
	s_mov_b64 vcc, s[46:47]
	v_cndmask_b32_e32 v155, v100, v155, vcc
	v_readlane_b32 s30, v255, 11
	v_readlane_b32 s31, v255, 12
	s_and_b64 s[46:47], s[4:5], s[30:31]
	v_fmac_f32_e32 v70, 0x3e0293ee, v102
	s_mov_b64 vcc, s[46:47]
	v_cndmask_b32_e32 v70, v100, v70, vcc
	v_readlane_b32 s30, v255, 13
	v_readlane_b32 s31, v255, 14
	v_readlane_b32 s46, v255, 15
	s_and_b64 s[30:31], s[4:5], s[30:31]
	v_readlane_b32 s47, v255, 16
	s_and_b64 s[46:47], s[30:31], s[46:47]
	v_fmac_f32_e32 v156, 0x3e0293ee, v86
	s_mov_b64 vcc, s[46:47]
	v_cndmask_b32_e32 v156, v100, v156, vcc
	v_readlane_b32 s30, v255, 17
	v_readlane_b32 s31, v255, 18
	s_and_b64 s[46:47], s[4:5], s[30:31]
	v_fmac_f32_e32 v71, 0x3e0293ee, v103
	s_mov_b64 vcc, s[46:47]
	v_cndmask_b32_e32 v71, v100, v71, vcc
	v_readlane_b32 s30, v255, 19
	v_readlane_b32 s31, v255, 20
	v_readlane_b32 s46, v255, 21
	s_and_b64 s[30:31], s[4:5], s[30:31]
	v_readlane_b32 s47, v255, 22
	s_and_b64 s[46:47], s[30:31], s[46:47]
	v_fmac_f32_e32 v157, 0x3e0293ee, v87
	s_mov_b64 vcc, s[46:47]
	v_cndmask_b32_e32 v157, v100, v157, vcc
	v_readlane_b32 s30, v255, 23
	v_readlane_b32 s31, v255, 24
	s_and_b64 s[46:47], s[4:5], s[30:31]
	v_fmac_f32_e32 v72, 0x3e0293ee, v104
	s_mov_b64 vcc, s[46:47]
	v_cndmask_b32_e32 v72, v100, v72, vcc
	v_readlane_b32 s30, v255, 25
	v_readlane_b32 s31, v255, 26
	v_readlane_b32 s46, v255, 27
	s_and_b64 s[30:31], s[4:5], s[30:31]
	v_readlane_b32 s47, v255, 28
	s_and_b64 s[46:47], s[30:31], s[46:47]
	v_fmac_f32_e32 v158, 0x3e0293ee, v88
	s_mov_b64 vcc, s[46:47]
	v_cndmask_b32_e32 v158, v100, v158, vcc
	v_readlane_b32 s30, v255, 29
	v_readlane_b32 s31, v255, 30
	s_and_b64 s[46:47], s[4:5], s[30:31]
	v_fmac_f32_e32 v73, 0x3e0293ee, v105
	s_mov_b64 vcc, s[46:47]
	v_cndmask_b32_e32 v73, v100, v73, vcc
	s_and_b64 s[30:31], s[4:5], s[48:49]
	s_and_b64 s[46:47], s[30:31], s[50:51]
	v_fmac_f32_e32 v159, 0x3e0293ee, v89
	s_mov_b64 vcc, s[46:47]
	v_cndmask_b32_e32 v159, v100, v159, vcc
	s_and_b64 s[46:47], s[4:5], s[52:53]
	v_fmac_f32_e32 v74, 0x3e0293ee, v106
	s_mov_b64 vcc, s[46:47]
	v_cndmask_b32_e32 v74, v100, v74, vcc
	s_and_b64 s[30:31], s[4:5], s[54:55]
	s_and_b64 s[46:47], s[30:31], s[56:57]
	v_fmac_f32_e32 v160, 0x3e0293ee, v90
	s_mov_b64 vcc, s[46:47]
	v_cndmask_b32_e32 v160, v100, v160, vcc
	s_and_b64 s[46:47], s[4:5], s[58:59]
	v_fmac_f32_e32 v75, 0x3e0293ee, v107
	s_mov_b64 vcc, s[46:47]
	v_cndmask_b32_e32 v75, v100, v75, vcc
	s_and_b64 s[30:31], s[4:5], s[60:61]
	s_and_b64 s[46:47], s[30:31], s[62:63]
	v_fmac_f32_e32 v161, 0x3e0293ee, v91
	s_mov_b64 vcc, s[46:47]
	v_cndmask_b32_e32 v161, v100, v161, vcc
	s_and_b64 s[46:47], s[4:5], s[28:29]
	v_fmac_f32_e32 v76, 0x3e0293ee, v108
	s_mov_b64 vcc, s[46:47]
	v_cndmask_b32_e32 v76, v100, v76, vcc
	s_and_b64 s[46:47], s[4:5], s[64:65]
	v_fmac_f32_e32 v162, 0x3e0293ee, v92
	s_mov_b64 vcc, s[46:47]
	v_cndmask_b32_e32 v162, v100, v162, vcc
	s_and_b64 s[30:31], s[4:5], s[66:67]
	s_and_b64 s[46:47], s[30:31], s[68:69]
	v_fmac_f32_e32 v77, 0x3e0293ee, v109
	s_mov_b64 vcc, s[46:47]
	v_cndmask_b32_e32 v77, v100, v77, vcc
	s_and_b64 s[46:47], s[4:5], s[70:71]
	v_fmac_f32_e32 v163, 0x3e0293ee, v93
	s_mov_b64 vcc, s[46:47]
	v_cndmask_b32_e32 v163, v100, v163, vcc
	s_and_b64 s[30:31], s[4:5], s[72:73]
	s_and_b64 s[46:47], s[30:31], s[74:75]
	v_fmac_f32_e32 v78, 0x3e0293ee, v110
	s_mov_b64 vcc, s[46:47]
	v_cndmask_b32_e32 v78, v100, v78, vcc
	s_and_b64 s[46:47], s[4:5], s[76:77]
	v_fmac_f32_e32 v164, 0x3e0293ee, v94
	s_mov_b64 vcc, s[46:47]
	v_cndmask_b32_e32 v164, v100, v164, vcc
	s_and_b64 s[30:31], s[4:5], s[78:79]
	s_and_b64 s[46:47], s[30:31], s[80:81]
	v_fmac_f32_e32 v79, 0x3e0293ee, v111
	s_mov_b64 vcc, s[46:47]
	v_cndmask_b32_e32 v79, v100, v79, vcc
	s_and_b64 s[46:47], s[4:5], s[82:83]
	v_fmac_f32_e32 v165, 0x3e0293ee, v95
	s_mov_b64 vcc, s[46:47]
	v_cndmask_b32_e32 v165, v100, v165, vcc
	s_and_b64 s[30:31], s[4:5], s[84:85]
	s_and_b64 s[46:47], s[30:31], s[86:87]
	v_fmac_f32_e32 v80, 0x3e0293ee, v112
	s_mov_b64 vcc, s[46:47]
	v_cndmask_b32_e32 v80, v100, v80, vcc
	s_and_b64 s[46:47], s[4:5], s[88:89]
	v_fmac_f32_e32 v166, 0x3e0293ee, v96
	s_mov_b64 vcc, s[46:47]
	v_cndmask_b32_e32 v166, v100, v166, vcc
	s_and_b64 s[30:31], s[4:5], s[90:91]
	s_and_b64 s[46:47], s[30:31], s[92:93]
	v_fmac_f32_e32 v81, 0x3e0293ee, v113
	s_mov_b64 vcc, s[46:47]
	v_cndmask_b32_e32 v81, v100, v81, vcc
	s_and_b64 s[46:47], s[4:5], s[94:95]
	v_fmac_f32_e32 v167, 0x3e0293ee, v97
	s_mov_b64 vcc, s[46:47]
	v_cndmask_b32_e32 v167, v100, v167, vcc
	s_and_b64 s[30:31], s[4:5], s[96:97]
	s_and_b64 s[46:47], s[30:31], s[14:15]
	v_fmac_f32_e32 v82, 0x3e0293ee, v114
	s_mov_b64 vcc, s[46:47]
	v_cndmask_b32_e32 v82, v100, v82, vcc
	s_and_b64 s[46:47], s[4:5], s[10:11]
	v_fmac_f32_e32 v151, 0x3e0293ee, v98
	s_mov_b64 vcc, s[46:47]
	v_cndmask_b32_e32 v151, v100, v151, vcc
	s_and_b64 s[30:31], s[4:5], s[0:1]
	s_and_b64 s[46:47], s[30:31], s[8:9]
	v_fmac_f32_e32 v83, 0x3e0293ee, v115
	s_mov_b64 vcc, s[46:47]
	v_cndmask_b32_e32 v83, v100, v83, vcc
	s_and_b64 s[30:31], s[4:5], s[6:7]
	v_fmac_f32_e32 v153, 0x3e0293ee, v99
	s_mov_b64 vcc, s[30:31]
	v_cndmask_b32_e32 v153, v100, v153, vcc

.LBB0_877:
	v_mov_b64_e32 v[4:5], 0x300
	s_ashr_i32 s15, s14, 31
	v_cmp_lt_i64_e32 vcc, s[16:17], v[4:5]
	s_lshl_b64 s[16:17], s[14:15], 20
	s_add_u32 s16, s27, s16
	s_addc_u32 s17, s28, s17
	s_and_b64 s[18:19], vcc, exec
	s_cselect_b32 s15, s17, s21
	s_cselect_b32 s44, s16, s20
	s_ashr_i32 s13, s12, 31
	s_lshl_b64 s[18:19], s[12:13], 20
	s_add_u32 s18, s29, s18
	s_addc_u32 s19, s30, s19
	s_and_b64 s[24:25], vcc, exec
	s_cselect_b32 s13, s19, s23
	s_cselect_b32 s45, s18, s22
	s_add_u32 s20, s20, 0x80080
	s_addc_u32 s21, s21, 0
	s_add_u32 s46, s22, 0x100
	s_addc_u32 s47, s23, 0
	s_mov_b32 s48, -2
	v_mov_b64_e32 v[4:5], 0
	v_mov_b64_e32 v[6:7], 0
	v_mov_b64_e32 v[8:9], 0
	v_mov_b64_e32 v[10:11], 0
	v_mov_b64_e32 v[12:13], 0
	v_mov_b64_e32 v[14:15], 0
	v_mov_b64_e32 v[16:17], 0
	v_mov_b64_e32 v[18:19], 0
	v_mov_b64_e32 v[20:21], 0
	v_mov_b64_e32 v[22:23], 0
	v_mov_b64_e32 v[24:25], 0
	v_mov_b64_e32 v[26:27], 0
	v_mov_b64_e32 v[28:29], 0
	v_mov_b64_e32 v[30:31], 0
	v_mov_b64_e32 v[32:33], 0
	v_mov_b64_e32 v[34:35], 0
	v_mov_b64_e32 v[36:37], 0
	v_mov_b64_e32 v[38:39], 0
	v_mov_b64_e32 v[40:41], 0
	v_mov_b64_e32 v[42:43], 0
	v_mov_b64_e32 v[44:45], 0
	v_mov_b64_e32 v[46:47], 0
	v_mov_b64_e32 v[48:49], 0
	v_mov_b64_e32 v[50:51], 0
	v_mov_b64_e32 v[52:53], 0
	v_mov_b64_e32 v[54:55], 0
	v_mov_b64_e32 v[56:57], 0
	v_mov_b64_e32 v[58:59], 0
	v_mov_b64_e32 v[60:61], 0
	v_mov_b64_e32 v[62:63], 0
	v_mov_b64_e32 v[64:65], 0
	v_mov_b64_e32 v[66:67], 0
	v_mov_b64_e32 v[68:69], 0
	v_mov_b64_e32 v[70:71], 0
	v_mov_b64_e32 v[72:73], 0
	v_mov_b64_e32 v[74:75], 0
	v_mov_b64_e32 v[76:77], 0
	v_mov_b64_e32 v[78:79], 0
	v_mov_b64_e32 v[80:81], 0
	v_mov_b64_e32 v[82:83], 0
	v_mov_b64_e32 v[84:85], 0
	v_mov_b64_e32 v[86:87], 0
	v_mov_b64_e32 v[88:89], 0
	v_mov_b64_e32 v[90:91], 0
	v_mov_b64_e32 v[92:93], 0
	v_mov_b64_e32 v[94:95], 0
	v_mov_b64_e32 v[96:97], 0
	v_mov_b64_e32 v[98:99], 0
	v_mov_b64_e32 v[100:101], 0
	v_mov_b64_e32 v[102:103], 0
	v_mov_b64_e32 v[104:105], 0
	v_mov_b64_e32 v[106:107], 0
	v_mov_b64_e32 v[108:109], 0
	v_mov_b64_e32 v[110:111], 0
	v_mov_b64_e32 v[112:113], 0
	v_mov_b64_e32 v[114:115], 0
	v_mov_b64_e32 v[116:117], 0
	v_mov_b64_e32 v[118:119], 0
	v_mov_b64_e32 v[120:121], 0
	v_mov_b64_e32 v[122:123], 0
	v_mov_b64_e32 v[124:125], 0
	v_mov_b64_e32 v[126:127], 0
	v_mov_b64_e32 v[128:129], 0
	v_mov_b64_e32 v[130:131], 0

.LBB0_1001:
	v_mov_b64_e32 v[4:5], 0x1080
	s_ashr_i32 s21, s20, 31
	v_cmp_lt_i64_e32 vcc, s[22:23], v[4:5]
	s_lshl_b64 s[22:23], s[20:21], 20
	s_add_u32 s22, s37, s22
	s_addc_u32 s23, s38, s23
	s_and_b64 s[24:25], vcc, exec
	s_cselect_b32 s21, s23, s27
	s_cselect_b32 s53, s22, s26
	s_ashr_i32 s19, s18, 31
	s_lshl_b64 s[24:25], s[18:19], 20
	s_add_u32 s24, s39, s24
	s_addc_u32 s25, s40, s25
	s_and_b64 s[30:31], vcc, exec
	s_cselect_b32 s19, s25, s29
	s_cselect_b32 s54, s24, s28
	s_add_u32 s55, s28, 0x100
	s_addc_u32 s56, s29, 0
	s_mov_b32 s57, -2
	v_mov_b64_e32 v[4:5], 0
	v_mov_b64_e32 v[6:7], 0
	v_mov_b64_e32 v[8:9], 0
	v_mov_b64_e32 v[10:11], 0
	v_mov_b64_e32 v[12:13], 0
	v_mov_b64_e32 v[14:15], 0
	v_mov_b64_e32 v[16:17], 0
	v_mov_b64_e32 v[18:19], 0
	v_mov_b64_e32 v[20:21], 0
	v_mov_b64_e32 v[22:23], 0
	v_mov_b64_e32 v[24:25], 0
	v_mov_b64_e32 v[26:27], 0
	v_mov_b64_e32 v[28:29], 0
	v_mov_b64_e32 v[30:31], 0
	v_mov_b64_e32 v[32:33], 0
	v_mov_b64_e32 v[34:35], 0
	v_mov_b64_e32 v[36:37], 0
	v_mov_b64_e32 v[38:39], 0
	v_mov_b64_e32 v[40:41], 0
	v_mov_b64_e32 v[42:43], 0
	v_mov_b64_e32 v[60:61], 0
	v_mov_b64_e32 v[62:63], 0
	v_mov_b64_e32 v[64:65], 0
	v_mov_b64_e32 v[66:67], 0
	v_mov_b64_e32 v[84:85], 0
	v_mov_b64_e32 v[86:87], 0
	v_mov_b64_e32 v[88:89], 0
	v_mov_b64_e32 v[90:91], 0
	v_mov_b64_e32 v[92:93], 0
	v_mov_b64_e32 v[94:95], 0
	v_mov_b64_e32 v[96:97], 0
	v_mov_b64_e32 v[98:99], 0
	v_mov_b64_e32 v[100:101], 0
	v_mov_b64_e32 v[102:103], 0
	v_mov_b64_e32 v[104:105], 0
	v_mov_b64_e32 v[106:107], 0
	v_mov_b64_e32 v[108:109], 0
	v_mov_b64_e32 v[110:111], 0
	v_mov_b64_e32 v[112:113], 0
	v_mov_b64_e32 v[114:115], 0
	v_mov_b64_e32 v[116:117], 0
	v_mov_b64_e32 v[118:119], 0
	v_mov_b64_e32 v[120:121], 0
	v_mov_b64_e32 v[122:123], 0
	v_mov_b64_e32 v[124:125], 0
	v_mov_b64_e32 v[126:127], 0
	v_mov_b64_e32 v[128:129], 0
	v_mov_b64_e32 v[130:131], 0
	v_mov_b64_e32 v[132:133], 0
	v_mov_b64_e32 v[134:135], 0
	v_mov_b64_e32 v[136:137], 0
	v_mov_b64_e32 v[138:139], 0
	v_mov_b64_e32 v[140:141], 0
	v_mov_b64_e32 v[142:143], 0
	v_mov_b64_e32 v[144:145], 0
	v_mov_b64_e32 v[146:147], 0
	v_mov_b64_e32 v[148:149], 0
	v_mov_b64_e32 v[150:151], 0
	v_mov_b64_e32 v[152:153], 0
	v_mov_b64_e32 v[154:155], 0
	v_mov_b64_e32 v[156:157], 0
	v_mov_b64_e32 v[158:159], 0
	v_mov_b64_e32 v[160:161], 0
	v_mov_b64_e32 v[162:163], 0

.LBB0_1179:
	s_add_u32 s42, s16, 0x100
	s_addc_u32 s43, s17, 0
	s_mov_b32 s44, -2
	v_mov_b64_e32 v[4:5], 0
	v_mov_b64_e32 v[6:7], 0
	v_mov_b64_e32 v[8:9], 0
	v_mov_b64_e32 v[10:11], 0
	v_mov_b64_e32 v[12:13], 0
	v_mov_b64_e32 v[14:15], 0
	v_mov_b64_e32 v[16:17], 0
	v_mov_b64_e32 v[18:19], 0
	v_mov_b64_e32 v[20:21], 0
	v_mov_b64_e32 v[22:23], 0
	v_mov_b64_e32 v[24:25], 0
	v_mov_b64_e32 v[26:27], 0
	v_mov_b64_e32 v[28:29], 0
	v_mov_b64_e32 v[30:31], 0
	v_mov_b64_e32 v[32:33], 0
	v_mov_b64_e32 v[34:35], 0
	v_mov_b64_e32 v[36:37], 0
	v_mov_b64_e32 v[38:39], 0
	v_mov_b64_e32 v[40:41], 0
	v_mov_b64_e32 v[42:43], 0
	v_mov_b64_e32 v[44:45], 0
	v_mov_b64_e32 v[46:47], 0
	v_mov_b64_e32 v[48:49], 0
	v_mov_b64_e32 v[50:51], 0
	v_mov_b64_e32 v[52:53], 0
	v_mov_b64_e32 v[54:55], 0
	v_mov_b64_e32 v[56:57], 0
	v_mov_b64_e32 v[58:59], 0
	v_mov_b64_e32 v[60:61], 0
	v_mov_b64_e32 v[62:63], 0
	v_mov_b64_e32 v[64:65], 0
	v_mov_b64_e32 v[66:67], 0
	v_mov_b64_e32 v[68:69], 0
	v_mov_b64_e32 v[70:71], 0
	v_mov_b64_e32 v[72:73], 0
	v_mov_b64_e32 v[74:75], 0
	v_mov_b64_e32 v[76:77], 0
	v_mov_b64_e32 v[78:79], 0
	v_mov_b64_e32 v[80:81], 0
	v_mov_b64_e32 v[82:83], 0
	v_mov_b64_e32 v[84:85], 0
	v_mov_b64_e32 v[86:87], 0
	v_mov_b64_e32 v[88:89], 0
	v_mov_b64_e32 v[90:91], 0
	v_mov_b64_e32 v[92:93], 0
	v_mov_b64_e32 v[94:95], 0
	v_mov_b64_e32 v[96:97], 0
	v_mov_b64_e32 v[98:99], 0
	v_mov_b64_e32 v[100:101], 0
	v_mov_b64_e32 v[102:103], 0
	v_mov_b64_e32 v[104:105], 0
	v_mov_b64_e32 v[106:107], 0
	v_mov_b64_e32 v[108:109], 0
	v_mov_b64_e32 v[110:111], 0
	v_mov_b64_e32 v[112:113], 0
	v_mov_b64_e32 v[114:115], 0
	v_mov_b64_e32 v[116:117], 0
	v_mov_b64_e32 v[118:119], 0
	v_mov_b64_e32 v[120:121], 0
	v_mov_b64_e32 v[122:123], 0
	v_mov_b64_e32 v[124:125], 0
	v_mov_b64_e32 v[126:127], 0
	v_mov_b64_e32 v[128:129], 0
	v_mov_b64_e32 v[130:131], 0
